# M1 item: the 16 per-row weight broadcasts issued together (one LDS wait instead of sixteen)
# speedup vs baseline: 1.0027x; 1.0004x over previous
.LBB0_313:
	s_or_b64 exec, exec, s[0:1]
	v_sub_f32_e32 v65, v65, v66
	v_mul_f32_e32 v65, 0x3fb8aa3b, v65
	s_waitcnt lgkmcnt(0)
	v_exp_f32_e32 v81, v65
	v_or_b32_e32 v130, v237, v68
	v_lshlrev_b32_e32 v130, 2, v130
	v_or_b32_e32 v132, v237, v85
	v_lshlrev_b32_e32 v132, 2, v132
	v_or_b32_e32 v134, v237, v84
	v_lshlrev_b32_e32 v134, 2, v134
	v_or_b32_e32 v136, v237, v83
	v_lshlrev_b32_e32 v136, 2, v136
	v_or_b32_e32 v138, v237, v82
	v_lshlrev_b32_e32 v138, 2, v138
	v_or_b32_e32 v140, v237, v80
	v_lshlrev_b32_e32 v140, 2, v140
	v_or_b32_e32 v142, v237, v79
	v_lshlrev_b32_e32 v142, 2, v142
	v_or_b32_e32 v144, v237, v78
	v_lshlrev_b32_e32 v144, 2, v144
	v_or_b32_e32 v146, v237, v77
	v_lshlrev_b32_e32 v146, 2, v146
	v_or_b32_e32 v148, v237, v76
	v_lshlrev_b32_e32 v148, 2, v148
	v_or_b32_e32 v150, v237, v75
	v_lshlrev_b32_e32 v150, 2, v150
	v_or_b32_e32 v152, v237, v74
	v_lshlrev_b32_e32 v152, 2, v152
	v_or_b32_e32 v154, v237, v73
	v_lshlrev_b32_e32 v154, 2, v154
	v_or_b32_e32 v156, v237, v72
	v_lshlrev_b32_e32 v156, 2, v156
	v_or_b32_e32 v158, v237, v71
	v_lshlrev_b32_e32 v158, 2, v158
	v_or_b32_e32 v160, v237, v70
	v_lshlrev_b32_e32 v160, 2, v160
	ds_bpermute_b32 v130, v130, v81
	ds_bpermute_b32 v132, v132, v81
	ds_bpermute_b32 v134, v134, v81
	ds_bpermute_b32 v136, v136, v81
	ds_bpermute_b32 v138, v138, v81
	ds_bpermute_b32 v140, v140, v81
	ds_bpermute_b32 v142, v142, v81
	ds_bpermute_b32 v144, v144, v81
	ds_bpermute_b32 v146, v146, v81
	ds_bpermute_b32 v148, v148, v81
	ds_bpermute_b32 v150, v150, v81
	ds_bpermute_b32 v152, v152, v81
	ds_bpermute_b32 v154, v154, v81
	ds_bpermute_b32 v156, v156, v81
	ds_bpermute_b32 v158, v158, v81
	ds_bpermute_b32 v160, v160, v81
	s_and_saveexec_b64 s[0:1], s[38:39]
	s_xor_b64 s[0:1], exec, s[0:1]
	s_or_saveexec_b64 s[0:1], s[0:1]
	s_mov_b32 s4, 0x9000
	v_mul_lo_u32 v64, v64, s4
	v_add_u32_e32 v105, s24, v64
	v_add_u32_e32 v64, 0x4800, v105
	v_mov_b32_e32 v86, v64
	s_xor_b64 exec, exec, s[0:1]
	s_cbranch_execz .LBB0_317
	v_lshlrev_b32_e32 v86, 16, v60
	v_and_b32_e32 v87, 0xffff0000, v60
	s_waitcnt lgkmcnt(0)
	v_pk_mul_f32 v[86:87], v[130:131], v[86:87] op_sel_hi:[0,1]
	v_cvt_pk_bf16_f32 v60, v86, v87
	v_lshlrev_b32_e32 v86, 16, v61
	v_and_b32_e32 v87, 0xffff0000, v61
	v_pk_mul_f32 v[86:87], v[130:131], v[86:87] op_sel_hi:[0,1]
	v_cvt_pk_bf16_f32 v61, v86, v87
	v_lshlrev_b32_e32 v86, 16, v62
	v_and_b32_e32 v87, 0xffff0000, v62
	v_pk_mul_f32 v[86:87], v[130:131], v[86:87] op_sel_hi:[0,1]
	v_cvt_pk_bf16_f32 v62, v86, v87
	v_lshlrev_b32_e32 v86, 16, v63
	v_and_b32_e32 v87, 0xffff0000, v63
	v_pk_mul_f32 v[86:87], v[130:131], v[86:87] op_sel_hi:[0,1]
	v_cvt_pk_bf16_f32 v63, v86, v87
	v_mov_b32_e32 v86, v105
.LBB0_317:
	s_or_b64 exec, exec, s[0:1]
	v_mul_u32_u24_e32 v65, 0x120, v68
	s_waitcnt lgkmcnt(0)
	v_add3_u32 v66, v86, v112, v65
	ds_write_b128 v66, v[60:63]
	s_and_saveexec_b64 s[0:1], s[38:39]
	s_xor_b64 s[0:1], exec, s[0:1]
	s_or_saveexec_b64 s[0:1], s[0:1]
	v_mov_b32_e32 v61, v64
	s_xor_b64 exec, exec, s[0:1]
	s_cbranch_execz .LBB0_321
	v_lshlrev_b32_e32 v62, 16, v56
	v_and_b32_e32 v63, 0xffff0000, v56
	s_waitcnt lgkmcnt(0)
	v_pk_mul_f32 v[62:63], v[132:133], v[62:63] op_sel_hi:[0,1]
	v_cvt_pk_bf16_f32 v56, v62, v63
	v_lshlrev_b32_e32 v62, 16, v57
	v_and_b32_e32 v63, 0xffff0000, v57
	v_pk_mul_f32 v[62:63], v[132:133], v[62:63] op_sel_hi:[0,1]
	v_cvt_pk_bf16_f32 v57, v62, v63
	v_lshlrev_b32_e32 v62, 16, v58
	v_and_b32_e32 v63, 0xffff0000, v58
	v_pk_mul_f32 v[62:63], v[132:133], v[62:63] op_sel_hi:[0,1]
	v_cvt_pk_bf16_f32 v58, v62, v63
	v_lshlrev_b32_e32 v62, 16, v59
	v_and_b32_e32 v63, 0xffff0000, v59
	v_pk_mul_f32 v[60:61], v[132:133], v[62:63] op_sel_hi:[0,1]
	v_cvt_pk_bf16_f32 v59, v60, v61
	v_mov_b32_e32 v61, v105
.LBB0_321:
	s_or_b64 exec, exec, s[0:1]
	s_waitcnt lgkmcnt(0)
	v_add3_u32 v60, v61, v112, v65
	ds_write_b128 v60, v[56:59] offset:1152
	s_and_saveexec_b64 s[0:1], s[38:39]
	s_xor_b64 s[0:1], exec, s[0:1]
	s_or_saveexec_b64 s[0:1], s[0:1]
	v_mov_b32_e32 v57, v64
	s_xor_b64 exec, exec, s[0:1]
	s_cbranch_execz .LBB0_325
	v_lshlrev_b32_e32 v58, 16, v52
	v_and_b32_e32 v59, 0xffff0000, v52
	s_waitcnt lgkmcnt(0)
	v_pk_mul_f32 v[58:59], v[134:135], v[58:59] op_sel_hi:[0,1]
	v_cvt_pk_bf16_f32 v52, v58, v59
	v_lshlrev_b32_e32 v58, 16, v53
	v_and_b32_e32 v59, 0xffff0000, v53
	v_pk_mul_f32 v[58:59], v[134:135], v[58:59] op_sel_hi:[0,1]
	v_cvt_pk_bf16_f32 v53, v58, v59
	v_lshlrev_b32_e32 v58, 16, v54
	v_and_b32_e32 v59, 0xffff0000, v54
	v_pk_mul_f32 v[58:59], v[134:135], v[58:59] op_sel_hi:[0,1]
	v_cvt_pk_bf16_f32 v54, v58, v59
	v_lshlrev_b32_e32 v58, 16, v55
	v_and_b32_e32 v59, 0xffff0000, v55
	v_pk_mul_f32 v[56:57], v[134:135], v[58:59] op_sel_hi:[0,1]
	v_cvt_pk_bf16_f32 v55, v56, v57
	v_mov_b32_e32 v57, v105
.LBB0_325:
	s_or_b64 exec, exec, s[0:1]
	s_waitcnt lgkmcnt(0)
	v_add3_u32 v56, v57, v112, v65
	ds_write_b128 v56, v[52:55] offset:2304
	s_and_saveexec_b64 s[0:1], s[38:39]
	s_xor_b64 s[0:1], exec, s[0:1]
	s_or_saveexec_b64 s[0:1], s[0:1]
	v_mov_b32_e32 v53, v64
	s_xor_b64 exec, exec, s[0:1]
	s_cbranch_execz .LBB0_329
	v_lshlrev_b32_e32 v54, 16, v48
	v_and_b32_e32 v55, 0xffff0000, v48
	s_waitcnt lgkmcnt(0)
	v_pk_mul_f32 v[54:55], v[136:137], v[54:55] op_sel_hi:[0,1]
	v_cvt_pk_bf16_f32 v48, v54, v55
	v_lshlrev_b32_e32 v54, 16, v49
	v_and_b32_e32 v55, 0xffff0000, v49
	v_pk_mul_f32 v[54:55], v[136:137], v[54:55] op_sel_hi:[0,1]
	v_cvt_pk_bf16_f32 v49, v54, v55
	v_lshlrev_b32_e32 v54, 16, v50
	v_and_b32_e32 v55, 0xffff0000, v50
	v_pk_mul_f32 v[54:55], v[136:137], v[54:55] op_sel_hi:[0,1]
	v_cvt_pk_bf16_f32 v50, v54, v55
	v_lshlrev_b32_e32 v54, 16, v51
	v_and_b32_e32 v55, 0xffff0000, v51
	v_pk_mul_f32 v[52:53], v[136:137], v[54:55] op_sel_hi:[0,1]
	v_cvt_pk_bf16_f32 v51, v52, v53
	v_mov_b32_e32 v53, v105
.LBB0_329:
	s_or_b64 exec, exec, s[0:1]
	s_waitcnt lgkmcnt(0)
	v_add3_u32 v52, v53, v112, v65
	ds_write_b128 v52, v[48:51] offset:3456
	s_and_saveexec_b64 s[0:1], s[38:39]
	s_xor_b64 s[0:1], exec, s[0:1]
	s_or_saveexec_b64 s[0:1], s[0:1]
	v_mov_b32_e32 v49, v64
	s_xor_b64 exec, exec, s[0:1]
	s_cbranch_execz .LBB0_333
	v_lshlrev_b32_e32 v50, 16, v44
	v_and_b32_e32 v51, 0xffff0000, v44
	s_waitcnt lgkmcnt(0)
	v_pk_mul_f32 v[50:51], v[138:139], v[50:51] op_sel_hi:[0,1]
	v_cvt_pk_bf16_f32 v44, v50, v51
	v_lshlrev_b32_e32 v50, 16, v45
	v_and_b32_e32 v51, 0xffff0000, v45
	v_pk_mul_f32 v[50:51], v[138:139], v[50:51] op_sel_hi:[0,1]
	v_cvt_pk_bf16_f32 v45, v50, v51
	v_lshlrev_b32_e32 v50, 16, v46
	v_and_b32_e32 v51, 0xffff0000, v46
	v_pk_mul_f32 v[50:51], v[138:139], v[50:51] op_sel_hi:[0,1]
	v_cvt_pk_bf16_f32 v46, v50, v51
	v_lshlrev_b32_e32 v50, 16, v47
	v_and_b32_e32 v51, 0xffff0000, v47
	v_pk_mul_f32 v[48:49], v[138:139], v[50:51] op_sel_hi:[0,1]
	v_cvt_pk_bf16_f32 v47, v48, v49
	v_mov_b32_e32 v49, v105
.LBB0_333:
	s_or_b64 exec, exec, s[0:1]
	s_waitcnt lgkmcnt(0)
	v_add3_u32 v48, v49, v112, v65
	ds_write_b128 v48, v[44:47] offset:4608
	s_and_saveexec_b64 s[0:1], s[38:39]
	s_xor_b64 s[0:1], exec, s[0:1]
	s_or_saveexec_b64 s[0:1], s[0:1]
	v_mov_b32_e32 v45, v64
	s_xor_b64 exec, exec, s[0:1]
	s_cbranch_execz .LBB0_337
	v_lshlrev_b32_e32 v46, 16, v40
	v_and_b32_e32 v47, 0xffff0000, v40
	s_waitcnt lgkmcnt(0)
	v_pk_mul_f32 v[46:47], v[140:141], v[46:47] op_sel_hi:[0,1]
	v_cvt_pk_bf16_f32 v40, v46, v47
	v_lshlrev_b32_e32 v46, 16, v41
	v_and_b32_e32 v47, 0xffff0000, v41
	v_pk_mul_f32 v[46:47], v[140:141], v[46:47] op_sel_hi:[0,1]
	v_cvt_pk_bf16_f32 v41, v46, v47
	v_lshlrev_b32_e32 v46, 16, v42
	v_and_b32_e32 v47, 0xffff0000, v42
	v_pk_mul_f32 v[46:47], v[140:141], v[46:47] op_sel_hi:[0,1]
	v_cvt_pk_bf16_f32 v42, v46, v47
	v_lshlrev_b32_e32 v46, 16, v43
	v_and_b32_e32 v47, 0xffff0000, v43
	v_pk_mul_f32 v[44:45], v[140:141], v[46:47] op_sel_hi:[0,1]
	v_cvt_pk_bf16_f32 v43, v44, v45
	v_mov_b32_e32 v45, v105
.LBB0_337:
	s_or_b64 exec, exec, s[0:1]
	s_waitcnt lgkmcnt(0)
	v_add3_u32 v44, v45, v112, v65
	ds_write_b128 v44, v[40:43] offset:5760
	s_and_saveexec_b64 s[0:1], s[38:39]
	s_xor_b64 s[0:1], exec, s[0:1]
	s_or_saveexec_b64 s[0:1], s[0:1]
	v_mov_b32_e32 v41, v64
	s_xor_b64 exec, exec, s[0:1]
	s_cbranch_execz .LBB0_341
	v_lshlrev_b32_e32 v42, 16, v36
	v_and_b32_e32 v43, 0xffff0000, v36
	s_waitcnt lgkmcnt(0)
	v_pk_mul_f32 v[42:43], v[142:143], v[42:43] op_sel_hi:[0,1]
	v_cvt_pk_bf16_f32 v36, v42, v43
	v_lshlrev_b32_e32 v42, 16, v37
	v_and_b32_e32 v43, 0xffff0000, v37
	v_pk_mul_f32 v[42:43], v[142:143], v[42:43] op_sel_hi:[0,1]
	v_cvt_pk_bf16_f32 v37, v42, v43
	v_lshlrev_b32_e32 v42, 16, v38
	v_and_b32_e32 v43, 0xffff0000, v38
	v_pk_mul_f32 v[42:43], v[142:143], v[42:43] op_sel_hi:[0,1]
	v_cvt_pk_bf16_f32 v38, v42, v43
	v_lshlrev_b32_e32 v42, 16, v39
	v_and_b32_e32 v43, 0xffff0000, v39
	v_pk_mul_f32 v[40:41], v[142:143], v[42:43] op_sel_hi:[0,1]
	v_cvt_pk_bf16_f32 v39, v40, v41
	v_mov_b32_e32 v41, v105
.LBB0_341:
	s_or_b64 exec, exec, s[0:1]
	s_waitcnt lgkmcnt(0)
	v_add3_u32 v40, v41, v112, v65
	ds_write_b128 v40, v[36:39] offset:6912
	s_and_saveexec_b64 s[0:1], s[38:39]
	s_xor_b64 s[0:1], exec, s[0:1]
	s_or_saveexec_b64 s[0:1], s[0:1]
	v_mov_b32_e32 v37, v64
	s_xor_b64 exec, exec, s[0:1]
	s_cbranch_execz .LBB0_345
	v_lshlrev_b32_e32 v38, 16, v32
	v_and_b32_e32 v39, 0xffff0000, v32
	s_waitcnt lgkmcnt(0)
	v_pk_mul_f32 v[38:39], v[144:145], v[38:39] op_sel_hi:[0,1]
	v_cvt_pk_bf16_f32 v32, v38, v39
	v_lshlrev_b32_e32 v38, 16, v33
	v_and_b32_e32 v39, 0xffff0000, v33
	v_pk_mul_f32 v[38:39], v[144:145], v[38:39] op_sel_hi:[0,1]
	v_cvt_pk_bf16_f32 v33, v38, v39
	v_lshlrev_b32_e32 v38, 16, v34
	v_and_b32_e32 v39, 0xffff0000, v34
	v_pk_mul_f32 v[38:39], v[144:145], v[38:39] op_sel_hi:[0,1]
	v_cvt_pk_bf16_f32 v34, v38, v39
	v_lshlrev_b32_e32 v38, 16, v35
	v_and_b32_e32 v39, 0xffff0000, v35
	v_pk_mul_f32 v[36:37], v[144:145], v[38:39] op_sel_hi:[0,1]
	v_cvt_pk_bf16_f32 v35, v36, v37
	v_mov_b32_e32 v37, v105
.LBB0_345:
	s_or_b64 exec, exec, s[0:1]
	s_waitcnt lgkmcnt(0)
	v_add3_u32 v36, v37, v112, v65
	ds_write_b128 v36, v[32:35] offset:8064
	s_and_saveexec_b64 s[0:1], s[38:39]
	s_xor_b64 s[0:1], exec, s[0:1]
	s_or_saveexec_b64 s[0:1], s[0:1]
	v_mov_b32_e32 v33, v64
	s_xor_b64 exec, exec, s[0:1]
	s_cbranch_execz .LBB0_349
	v_lshlrev_b32_e32 v34, 16, v28
	v_and_b32_e32 v35, 0xffff0000, v28
	s_waitcnt lgkmcnt(0)
	v_pk_mul_f32 v[34:35], v[146:147], v[34:35] op_sel_hi:[0,1]
	v_cvt_pk_bf16_f32 v28, v34, v35
	v_lshlrev_b32_e32 v34, 16, v29
	v_and_b32_e32 v35, 0xffff0000, v29
	v_pk_mul_f32 v[34:35], v[146:147], v[34:35] op_sel_hi:[0,1]
	v_cvt_pk_bf16_f32 v29, v34, v35
	v_lshlrev_b32_e32 v34, 16, v30
	v_and_b32_e32 v35, 0xffff0000, v30
	v_pk_mul_f32 v[34:35], v[146:147], v[34:35] op_sel_hi:[0,1]
	v_cvt_pk_bf16_f32 v30, v34, v35
	v_lshlrev_b32_e32 v34, 16, v31
	v_and_b32_e32 v35, 0xffff0000, v31
	v_pk_mul_f32 v[32:33], v[146:147], v[34:35] op_sel_hi:[0,1]
	v_cvt_pk_bf16_f32 v31, v32, v33
	v_mov_b32_e32 v33, v105
.LBB0_349:
	s_or_b64 exec, exec, s[0:1]
	s_waitcnt lgkmcnt(0)
	v_add3_u32 v32, v33, v112, v65
	ds_write_b128 v32, v[28:31] offset:9216
	s_and_saveexec_b64 s[0:1], s[38:39]
	s_xor_b64 s[0:1], exec, s[0:1]
	s_or_saveexec_b64 s[0:1], s[0:1]
	v_mov_b32_e32 v29, v64
	s_xor_b64 exec, exec, s[0:1]
	s_cbranch_execz .LBB0_353
	v_lshlrev_b32_e32 v30, 16, v24
	v_and_b32_e32 v31, 0xffff0000, v24
	s_waitcnt lgkmcnt(0)
	v_pk_mul_f32 v[30:31], v[148:149], v[30:31] op_sel_hi:[0,1]
	v_cvt_pk_bf16_f32 v24, v30, v31
	v_lshlrev_b32_e32 v30, 16, v25
	v_and_b32_e32 v31, 0xffff0000, v25
	v_pk_mul_f32 v[30:31], v[148:149], v[30:31] op_sel_hi:[0,1]
	v_cvt_pk_bf16_f32 v25, v30, v31
	v_lshlrev_b32_e32 v30, 16, v26
	v_and_b32_e32 v31, 0xffff0000, v26
	v_pk_mul_f32 v[30:31], v[148:149], v[30:31] op_sel_hi:[0,1]
	v_cvt_pk_bf16_f32 v26, v30, v31
	v_lshlrev_b32_e32 v30, 16, v27
	v_and_b32_e32 v31, 0xffff0000, v27
	v_pk_mul_f32 v[28:29], v[148:149], v[30:31] op_sel_hi:[0,1]
	v_cvt_pk_bf16_f32 v27, v28, v29
	v_mov_b32_e32 v29, v105
.LBB0_353:
	s_or_b64 exec, exec, s[0:1]
	s_waitcnt lgkmcnt(0)
	v_add3_u32 v28, v29, v112, v65
	ds_write_b128 v28, v[24:27] offset:10368
	s_and_saveexec_b64 s[0:1], s[38:39]
	s_xor_b64 s[0:1], exec, s[0:1]
	s_or_saveexec_b64 s[0:1], s[0:1]
	v_mov_b32_e32 v25, v64
	s_xor_b64 exec, exec, s[0:1]
	s_cbranch_execz .LBB0_357
	v_lshlrev_b32_e32 v26, 16, v20
	v_and_b32_e32 v27, 0xffff0000, v20
	s_waitcnt lgkmcnt(0)
	v_pk_mul_f32 v[26:27], v[150:151], v[26:27] op_sel_hi:[0,1]
	v_cvt_pk_bf16_f32 v20, v26, v27
	v_lshlrev_b32_e32 v26, 16, v21
	v_and_b32_e32 v27, 0xffff0000, v21
	v_pk_mul_f32 v[26:27], v[150:151], v[26:27] op_sel_hi:[0,1]
	v_cvt_pk_bf16_f32 v21, v26, v27
	v_lshlrev_b32_e32 v26, 16, v22
	v_and_b32_e32 v27, 0xffff0000, v22
	v_pk_mul_f32 v[26:27], v[150:151], v[26:27] op_sel_hi:[0,1]
	v_cvt_pk_bf16_f32 v22, v26, v27
	v_lshlrev_b32_e32 v26, 16, v23
	v_and_b32_e32 v27, 0xffff0000, v23
	v_pk_mul_f32 v[24:25], v[150:151], v[26:27] op_sel_hi:[0,1]
	v_cvt_pk_bf16_f32 v23, v24, v25
	v_mov_b32_e32 v25, v105
.LBB0_357:
	s_or_b64 exec, exec, s[0:1]
	s_waitcnt lgkmcnt(0)
	v_add3_u32 v24, v25, v112, v65
	ds_write_b128 v24, v[20:23] offset:11520
	s_and_saveexec_b64 s[0:1], s[38:39]
	s_xor_b64 s[0:1], exec, s[0:1]
	s_or_saveexec_b64 s[0:1], s[0:1]
	v_mov_b32_e32 v21, v64
	s_xor_b64 exec, exec, s[0:1]
	s_cbranch_execz .LBB0_361
	v_lshlrev_b32_e32 v22, 16, v16
	v_and_b32_e32 v23, 0xffff0000, v16
	s_waitcnt lgkmcnt(0)
	v_pk_mul_f32 v[22:23], v[152:153], v[22:23] op_sel_hi:[0,1]
	v_cvt_pk_bf16_f32 v16, v22, v23
	v_lshlrev_b32_e32 v22, 16, v17
	v_and_b32_e32 v23, 0xffff0000, v17
	v_pk_mul_f32 v[22:23], v[152:153], v[22:23] op_sel_hi:[0,1]
	v_cvt_pk_bf16_f32 v17, v22, v23
	v_lshlrev_b32_e32 v22, 16, v18
	v_and_b32_e32 v23, 0xffff0000, v18
	v_pk_mul_f32 v[22:23], v[152:153], v[22:23] op_sel_hi:[0,1]
	v_cvt_pk_bf16_f32 v18, v22, v23
	v_lshlrev_b32_e32 v22, 16, v19
	v_and_b32_e32 v23, 0xffff0000, v19
	v_pk_mul_f32 v[20:21], v[152:153], v[22:23] op_sel_hi:[0,1]
	v_cvt_pk_bf16_f32 v19, v20, v21
	v_mov_b32_e32 v21, v105
.LBB0_361:
	s_or_b64 exec, exec, s[0:1]
	s_waitcnt lgkmcnt(0)
	v_add3_u32 v20, v21, v112, v65
	ds_write_b128 v20, v[16:19] offset:12672
	s_and_saveexec_b64 s[0:1], s[38:39]
	s_xor_b64 s[0:1], exec, s[0:1]
	s_or_saveexec_b64 s[0:1], s[0:1]
	v_mov_b32_e32 v17, v64
	s_xor_b64 exec, exec, s[0:1]
	s_cbranch_execz .LBB0_365
	v_lshlrev_b32_e32 v18, 16, v12
	v_and_b32_e32 v19, 0xffff0000, v12
	s_waitcnt lgkmcnt(0)
	v_pk_mul_f32 v[18:19], v[154:155], v[18:19] op_sel_hi:[0,1]
	v_cvt_pk_bf16_f32 v12, v18, v19
	v_lshlrev_b32_e32 v18, 16, v13
	v_and_b32_e32 v19, 0xffff0000, v13
	v_pk_mul_f32 v[18:19], v[154:155], v[18:19] op_sel_hi:[0,1]
	v_cvt_pk_bf16_f32 v13, v18, v19
	v_lshlrev_b32_e32 v18, 16, v14
	v_and_b32_e32 v19, 0xffff0000, v14
	v_pk_mul_f32 v[18:19], v[154:155], v[18:19] op_sel_hi:[0,1]
	v_cvt_pk_bf16_f32 v14, v18, v19
	v_lshlrev_b32_e32 v18, 16, v15
	v_and_b32_e32 v19, 0xffff0000, v15
	v_pk_mul_f32 v[16:17], v[154:155], v[18:19] op_sel_hi:[0,1]
	v_cvt_pk_bf16_f32 v15, v16, v17
	v_mov_b32_e32 v17, v105
.LBB0_365:
	s_or_b64 exec, exec, s[0:1]
	s_waitcnt lgkmcnt(0)
	v_add3_u32 v16, v17, v112, v65
	ds_write_b128 v16, v[12:15] offset:13824
	s_and_saveexec_b64 s[0:1], s[38:39]
	s_xor_b64 s[0:1], exec, s[0:1]
	s_or_saveexec_b64 s[0:1], s[0:1]
	v_mov_b32_e32 v13, v64
	s_xor_b64 exec, exec, s[0:1]
	s_cbranch_execz .LBB0_369
	v_lshlrev_b32_e32 v14, 16, v8
	v_and_b32_e32 v15, 0xffff0000, v8
	s_waitcnt lgkmcnt(0)
	v_pk_mul_f32 v[14:15], v[156:157], v[14:15] op_sel_hi:[0,1]
	v_cvt_pk_bf16_f32 v8, v14, v15
	v_lshlrev_b32_e32 v14, 16, v9
	v_and_b32_e32 v15, 0xffff0000, v9
	v_pk_mul_f32 v[14:15], v[156:157], v[14:15] op_sel_hi:[0,1]
	v_cvt_pk_bf16_f32 v9, v14, v15
	v_lshlrev_b32_e32 v14, 16, v10
	v_and_b32_e32 v15, 0xffff0000, v10
	v_pk_mul_f32 v[14:15], v[156:157], v[14:15] op_sel_hi:[0,1]
	v_cvt_pk_bf16_f32 v10, v14, v15
	v_lshlrev_b32_e32 v14, 16, v11
	v_and_b32_e32 v15, 0xffff0000, v11
	v_pk_mul_f32 v[12:13], v[156:157], v[14:15] op_sel_hi:[0,1]
	v_cvt_pk_bf16_f32 v11, v12, v13
	v_mov_b32_e32 v13, v105
.LBB0_369:
	s_or_b64 exec, exec, s[0:1]
	s_waitcnt lgkmcnt(0)
	v_add3_u32 v12, v13, v112, v65
	ds_write_b128 v12, v[8:11] offset:14976
	s_and_saveexec_b64 s[0:1], s[38:39]
	s_xor_b64 s[0:1], exec, s[0:1]
	s_or_saveexec_b64 s[0:1], s[0:1]
	v_mov_b32_e32 v9, v64
	s_xor_b64 exec, exec, s[0:1]
	s_cbranch_execz .LBB0_373
	v_lshlrev_b32_e32 v10, 16, v4
	v_and_b32_e32 v11, 0xffff0000, v4
	s_waitcnt lgkmcnt(0)
	v_pk_mul_f32 v[10:11], v[158:159], v[10:11] op_sel_hi:[0,1]
	v_cvt_pk_bf16_f32 v4, v10, v11
	v_lshlrev_b32_e32 v10, 16, v5
	v_and_b32_e32 v11, 0xffff0000, v5
	v_pk_mul_f32 v[10:11], v[158:159], v[10:11] op_sel_hi:[0,1]
	v_cvt_pk_bf16_f32 v5, v10, v11
	v_lshlrev_b32_e32 v10, 16, v6
	v_and_b32_e32 v11, 0xffff0000, v6
	v_pk_mul_f32 v[10:11], v[158:159], v[10:11] op_sel_hi:[0,1]
	v_cvt_pk_bf16_f32 v6, v10, v11
	v_lshlrev_b32_e32 v10, 16, v7
	v_and_b32_e32 v11, 0xffff0000, v7
	v_pk_mul_f32 v[8:9], v[158:159], v[10:11] op_sel_hi:[0,1]
	v_cvt_pk_bf16_f32 v7, v8, v9
	v_mov_b32_e32 v9, v105
.LBB0_373:
	s_or_b64 exec, exec, s[0:1]
	s_waitcnt lgkmcnt(0)
	v_add3_u32 v8, v9, v112, v65
	ds_write_b128 v8, v[4:7] offset:16128
	s_and_saveexec_b64 s[0:1], s[38:39]
	s_xor_b64 s[0:1], exec, s[0:1]
	s_andn2_saveexec_b64 s[0:1], s[0:1]
	s_cbranch_execz .LBB0_377
	v_lshlrev_b32_e32 v6, 16, v0
	v_and_b32_e32 v7, 0xffff0000, v0
	s_waitcnt lgkmcnt(0)
	v_pk_mul_f32 v[6:7], v[160:161], v[6:7] op_sel_hi:[0,1]
	v_cvt_pk_bf16_f32 v0, v6, v7
	v_lshlrev_b32_e32 v6, 16, v1
	v_and_b32_e32 v7, 0xffff0000, v1
	v_pk_mul_f32 v[6:7], v[160:161], v[6:7] op_sel_hi:[0,1]
	v_cvt_pk_bf16_f32 v1, v6, v7
	v_lshlrev_b32_e32 v6, 16, v2
	v_and_b32_e32 v7, 0xffff0000, v2
	v_pk_mul_f32 v[6:7], v[160:161], v[6:7] op_sel_hi:[0,1]
	v_cvt_pk_bf16_f32 v2, v6, v7
	v_lshlrev_b32_e32 v6, 16, v3
	v_and_b32_e32 v7, 0xffff0000, v3
	v_pk_mul_f32 v[4:5], v[160:161], v[6:7] op_sel_hi:[0,1]
	v_cvt_pk_bf16_f32 v3, v4, v5
	v_mov_b32_e32 v64, v105
